# global loop: K/V LDS-DMA prefetch one step deeper (ring of 5/4 buffers)
# baseline (speedup 1.0000x reference)
; #define ATT_LAS __attribute__((address_space(3)))
; #define ATT_LDK(dst, buf) do { _Pragma("unroll") for (int d0_ = 0; d0_ < 4; ++d0_) { dst[2 * d0_] = *(const ATT_LAS bf16x8*)((buf) + kfrag + d0_ * 2048); dst[2 * d0_ + 1] = *(const ATT_LAS bf16x8*)((buf) + kfrag + d0_ * 2048 + 512); } } while (0)
; template <bool NOMAX> ...
;         const f32x16 zero16 = {};
;         u32x4 kreg, vreg; bf16x8 kf[8]; f32x16 c0, c1, e0, e1;
;         { const u32x4 k0 = *(const u32x4*)(kg + (size_t)ATT_TROW(0) * PITCH), k1 = *(const u32x4*)(kg + (size_t)ATT_TROW(1) * PITCH);
;           *(ATT_LAS u32x4*)(ATT_KBUF(0) + koff) = k0; *(ATT_LAS u32x4*)(ATT_KBUF(1) + koff) = k1; }
;         __syncthreads();
;         kreg = *(const u32x4*)(kg + (size_t)ATT_TROW(2) * PITCH); vreg = *(const u32x4*)(vg + (size_t)ATT_TROW(0) * PITCH);
;         ATT_LDK(kf, ATT_KBUF(0));
;         c0 = (f32x16){}; c1 = (f32x16){};
; #pragma unroll
;         for (int d0 = 0; d0 < 4; ++d0) { c0 = __builtin_amdgcn_mfma_f32_32x32x16_bf16(kf[2 * d0], qf[d0], c0, 0, 0, 0); c1 = __builtin_amdgcn_mfma_f32_32x32x16_bf16(kf[2 * d0 + 1], qf[d0], c1, 0, 0, 0); }
;         m = NOMAX ? 0.f : rowmax32(c0, c1);
; #pragma unroll
;         for (int r = 0; r < 16; ++r) { e0[r] = __builtin_amdgcn_exp2f(c0[r] - m); e1[r] = __builtin_amdgcn_exp2f(c1[r] - m); }
;         ATT_LDK(kf, ATT_KBUF(1));
;         *(ATT_LAS u32x4*)(ATT_KBUF(2) + koff) = kreg; *(ATT_LAS u32x4*)(ATT_VBUF(0) + voff) = vreg;
;         __syncthreads();
;         u32x4 kregB = kreg, vregB = vreg;
;         kreg = *(const u32x4*)(kg + (size_t)ATT_TROW(3) * PITCH); vreg = *(const u32x4*)(vg + (size_t)ATT_TROW(1) * PITCH);
;         int kb2 = 0;
.Lmk_entry_g:
	v_mov_b32_e32 v202, 0
	v_mov_b32_e32 v124, 0
	v_mov_b32_e32 v204, 0
	v_mov_b32_e32 v205, 0
	v_mov_b32_e32 v208, 0
	v_mov_b32_e32 v209, 0
	v_mov_b32_e32 v0, 0
	v_mov_b32_e32 v1, 0
	v_mov_b32_e32 v2, 0
	v_mov_b32_e32 v3, 0
	v_mov_b32_e32 v4, 0
	v_mov_b32_e32 v5, 0
	v_mov_b32_e32 v6, 0
	v_mov_b32_e32 v7, 0
	v_mov_b32_e32 v8, 0
	v_mov_b32_e32 v9, 0
	v_mov_b32_e32 v10, 0
	v_mov_b32_e32 v11, 0
	v_mov_b32_e32 v12, 0
	v_mov_b32_e32 v13, 0
	v_mov_b32_e32 v14, 0
	v_mov_b32_e32 v15, 0
	v_mov_b32_e32 v16, 0
	v_mov_b32_e32 v17, 0
	v_mov_b32_e32 v18, 0
	v_mov_b32_e32 v19, 0
	v_mov_b32_e32 v20, 0
	v_mov_b32_e32 v21, 0
	v_mov_b32_e32 v22, 0
	v_mov_b32_e32 v23, 0
	v_mov_b32_e32 v24, 0
	v_mov_b32_e32 v25, 0
	v_mov_b32_e32 v26, 0
	v_mov_b32_e32 v27, 0
	v_mov_b32_e32 v28, 0
	v_mov_b32_e32 v29, 0
	v_mov_b32_e32 v30, 0
	v_mov_b32_e32 v31, 0
	s_lshl_b32 s92, s93, 6
	s_add_i32 s84, s27, s92
	v_lshrrev_b32_e32 v116, 6, v192
	v_and_b32_e32 v117, 63, v192
	v_lshrrev_b32_e32 v118, 3, v117
	v_sub_u32_e32 v118, v118, v116
	v_mul_i32_i24_e32 v248, 0x8ff0, v118
	v_and_b32_e32 v118, 3, v116
	v_lshlrev_b32_e32 v118, 4, v118
	v_lshlrev_b32_e32 v119, 3, v116
	v_sub_u32_e32 v118, v118, v119
	v_bfe_u32 v119, v117, 3, 1
	v_bfe_u32 v242, v117, 4, 1
	v_bfe_u32 v243, v117, 5, 1
	v_add_u32_e32 v242, v119, v242
	v_lshl_add_u32 v242, v243, 1, v242
	v_lshl_add_u32 v118, v242, 1, v118
	v_lshrrev_b32_e32 v243, 2, v116
	v_sub_u32_e32 v243, v243, v119
	v_mul_i32_i24_e32 v118, 0x1200, v118
	v_lshl_add_u32 v249, v243, 6, v118
	v_readfirstlane_b32 s100, v116
	s_mov_b64 s[98:99], 0x48000
	s_lshl_b32 s100, s100, 10
	v_add_u32_e32 v253, s35, v231
	v_mad_i64_i32 v[244:245], s[80:81], s30, v215, v[198:199]
	v_ashrrev_i32_e32 v243, 31, v248
	v_mov_b32_e32 v242, v248
	v_lshl_add_u64 v[244:245], v[242:243], 0, v[244:245]
	v_mad_i64_i32 v[246:247], s[80:81], s30, v215, v[200:201]
	v_ashrrev_i32_e32 v243, 31, v249
	v_mov_b32_e32 v242, v249
	v_lshl_add_u64 v[246:247], v[242:243], 0, v[246:247]
	s_add_i32 s71, s71, 4
	s_add_i32 s81, s100, 0x0
	s_mov_b32 m0, s81
	s_nop 0
	global_load_lds_dwordx4 v[244:245], off
	v_lshl_add_u64 v[244:245], v[244:245], 0, s[98:99]
	s_add_i32 s81, s100, 0x2000
	s_mov_b32 m0, s81
	s_nop 0
	global_load_lds_dwordx4 v[244:245], off
	v_lshl_add_u64 v[244:245], v[244:245], 0, s[98:99]
	s_add_i32 s81, s100, 0x4000
	s_mov_b32 m0, s81
	s_nop 0
	global_load_lds_dwordx4 v[244:245], off
	v_lshl_add_u64 v[244:245], v[244:245], 0, s[98:99]
	s_add_i32 s81, s100, 0xe000
	s_mov_b32 m0, s81
	s_nop 0
	global_load_lds_dwordx4 v[244:245], off
	v_lshl_add_u64 v[244:245], v[244:245], 0, s[98:99]
	s_add_i32 s81, s100, 0x6000
	s_mov_b32 m0, s81
	s_nop 0
	global_load_lds_dwordx4 v[246:247], off
	v_lshl_add_u64 v[246:247], v[246:247], 0, s[98:99]
	s_add_i32 s81, s100, 0x8000
	s_mov_b32 m0, s81
	s_nop 0
	global_load_lds_dwordx4 v[246:247], off
	v_lshl_add_u64 v[246:247], v[246:247], 0, s[98:99]
	s_waitcnt vmcnt(0)
	s_waitcnt lgkmcnt(0)
	s_barrier
	s_mov_b32 s96, 4
	s_cmp_lg_u32 s96, 4
	s_cbranch_scc1 .Lgp_ks
	v_mad_i64_i32 v[244:245], s[80:81], s84, v215, v[198:199]
	v_ashrrev_i32_e32 v243, 31, v248
	v_mov_b32_e32 v242, v248
	v_lshl_add_u64 v[244:245], v[242:243], 0, v[244:245]
.Lgp_ks:
	s_mul_hi_u32 s80, s96, 0x33333334
	s_mul_i32 s80, s80, 5
	s_sub_u32 s80, s96, s80
	s_lshl_b32 s81, s80, 13
	s_cmp_eq_u32 s80, 3
	s_cselect_b32 s81, 0xe000, s81
	s_cmp_eq_u32 s80, 4
	s_cselect_b32 s81, 0x10000, s81
	s_add_i32 s81, s81, s100
	s_mov_b32 m0, s81
	s_nop 0
	global_load_lds_dwordx4 v[244:245], off
	v_lshl_add_u64 v[244:245], v[244:245], 0, s[98:99]
	s_mov_b32 s96, 2
	s_cmp_lg_u32 s96, 4
	s_cbranch_scc1 .Lgp_vs
	v_mad_i64_i32 v[246:247], s[80:81], s84, v215, v[200:201]
	v_ashrrev_i32_e32 v243, 31, v249
	v_mov_b32_e32 v242, v249
	v_lshl_add_u64 v[246:247], v[242:243], 0, v[246:247]
.Lgp_vs:
	s_and_b32 s80, s96, 3
	s_lshl_b32 s81, s80, 13
	s_cmp_eq_u32 s80, 2
	s_cselect_b32 s81, 0x6000, s81
	s_cmp_eq_u32 s80, 3
	s_cselect_b32 s81, 0xc000, s81
	s_add_i32 s81, s81, 0x6000
	s_add_i32 s81, s81, s100
	s_mov_b32 m0, s81
	s_nop 0
	global_load_lds_dwordx4 v[246:247], off
	v_lshl_add_u64 v[246:247], v[246:247], 0, s[98:99]
	v_mov_b32_e32 v243, v221
	ds_read_b128 v[128:131], v243
	ds_read_b128 v[132:135], v243 offset:512
	ds_read_b128 v[136:139], v243 offset:2048
	ds_read_b128 v[140:143], v243 offset:2560
	ds_read_b128 v[144:147], v243 offset:4096
	ds_read_b128 v[148:151], v243 offset:4608
	ds_read_b128 v[152:155], v243 offset:6144
	ds_read_b128 v[156:159], v243 offset:6656
	s_waitcnt lgkmcnt(7)
	v_mfma_f32_32x32x16_bf16 v[32:47], v[128:131], v[96:99], 0
	s_waitcnt lgkmcnt(6)
	v_mfma_f32_32x32x16_bf16 v[64:79], v[132:135], v[96:99], 0
	s_waitcnt lgkmcnt(5)
	v_mfma_f32_32x32x16_bf16 v[32:47], v[136:139], v[100:103], v[32:47]
	s_waitcnt lgkmcnt(4)
	v_mfma_f32_32x32x16_bf16 v[64:79], v[140:143], v[100:103], v[64:79]
	s_waitcnt lgkmcnt(3)
	v_mfma_f32_32x32x16_bf16 v[32:47], v[144:147], v[104:107], v[32:47]
	s_waitcnt lgkmcnt(2)
	v_mfma_f32_32x32x16_bf16 v[64:79], v[148:151], v[104:107], v[64:79]
	s_waitcnt lgkmcnt(1)
	v_mfma_f32_32x32x16_bf16 v[32:47], v[152:155], v[108:111], v[32:47]
	s_waitcnt lgkmcnt(0)
	v_mfma_f32_32x32x16_bf16 v[64:79], v[156:159], v[108:111], v[64:79]
	v_add_u32_e32 v243, 0x2000, v221
	ds_read_b128 v[128:131], v243
	ds_read_b128 v[132:135], v243 offset:512
	ds_read_b128 v[136:139], v243 offset:2048
	ds_read_b128 v[140:143], v243 offset:2560
	ds_read_b128 v[144:147], v243 offset:4096
	ds_read_b128 v[148:151], v243 offset:4608
	ds_read_b128 v[152:155], v243 offset:6144
	ds_read_b128 v[156:159], v243 offset:6656
	s_nop 2
	v_exp_f32_e32 v32, v32
	v_exp_f32_e32 v33, v33
	v_exp_f32_e32 v34, v34
	v_exp_f32_e32 v35, v35
	v_exp_f32_e32 v36, v36
	v_exp_f32_e32 v37, v37
	v_exp_f32_e32 v38, v38
	v_exp_f32_e32 v39, v39
	v_exp_f32_e32 v40, v40
	v_exp_f32_e32 v41, v41
	v_exp_f32_e32 v42, v42
	v_exp_f32_e32 v43, v43
	v_exp_f32_e32 v44, v44
	v_exp_f32_e32 v45, v45
	v_exp_f32_e32 v46, v46
	v_exp_f32_e32 v47, v47
	v_exp_f32_e32 v64, v64
	v_exp_f32_e32 v65, v65
	v_exp_f32_e32 v66, v66
	v_exp_f32_e32 v67, v67
	v_exp_f32_e32 v68, v68
	v_exp_f32_e32 v69, v69
	v_exp_f32_e32 v70, v70
	v_exp_f32_e32 v71, v71
	v_exp_f32_e32 v72, v72
	v_exp_f32_e32 v73, v73
	v_exp_f32_e32 v74, v74
	v_exp_f32_e32 v75, v75
	v_exp_f32_e32 v76, v76
	v_exp_f32_e32 v77, v77
	v_exp_f32_e32 v78, v78
	v_exp_f32_e32 v79, v79
	s_waitcnt lgkmcnt(0)
	s_barrier
	s_mov_b32 s7, 1
.Lg_loop:
	s_add_i32 s96, s7, 4
	s_cmp_lt_i32 s96, s71
	s_cselect_b64 s[82:83], -1, 0
	s_cbranch_scc0 .Lgo_nk
	s_cmp_lg_u32 s96, 4
	s_cbranch_scc1 .Lgo_ks
	v_mad_i64_i32 v[244:245], s[80:81], s84, v215, v[198:199]
	v_ashrrev_i32_e32 v243, 31, v248
	v_mov_b32_e32 v242, v248
	v_lshl_add_u64 v[244:245], v[242:243], 0, v[244:245]
.Lgo_ks:
	s_mul_hi_u32 s80, s96, 0x33333334
	s_mul_i32 s80, s80, 5
	s_sub_u32 s80, s96, s80
	s_lshl_b32 s81, s80, 13
	s_cmp_eq_u32 s80, 3
	s_cselect_b32 s81, 0xe000, s81
	s_cmp_eq_u32 s80, 4
	s_cselect_b32 s81, 0x10000, s81
	s_add_i32 s81, s81, s100
	s_mov_b32 m0, s81
	s_nop 0
	global_load_lds_dwordx4 v[244:245], off
	v_lshl_add_u64 v[244:245], v[244:245], 0, s[98:99]
.Lgo_nk:
	s_add_i32 s96, s7, 2
	s_cmp_lt_i32 s96, s71
	s_cbranch_scc0 .Lgo_nv
	s_cmp_lg_u32 s96, 4
	s_cbranch_scc1 .Lgo_vs
	v_mad_i64_i32 v[246:247], s[80:81], s84, v215, v[200:201]
	v_ashrrev_i32_e32 v243, 31, v249
	v_mov_b32_e32 v242, v249
	v_lshl_add_u64 v[246:247], v[242:243], 0, v[246:247]
.Lgo_vs:
	s_and_b32 s80, s96, 3
	s_lshl_b32 s81, s80, 13
	s_cmp_eq_u32 s80, 2
	s_cselect_b32 s81, 0x6000, s81
	s_cmp_eq_u32 s80, 3
	s_cselect_b32 s81, 0xc000, s81
	s_add_i32 s81, s81, 0x6000
	s_add_i32 s81, s81, s100
	s_mov_b32 m0, s81
	s_nop 0
	global_load_lds_dwordx4 v[246:247], off
	v_lshl_add_u64 v[246:247], v[246:247], 0, s[98:99]
.Lgo_nv:
	s_add_i32 s72, s7, 3
	s_and_b32 s80, s72, 3
	s_lshl_b32 s81, s80, 13
	s_cmp_eq_u32 s80, 2
	s_cselect_b32 s81, 0x6000, s81
	s_cmp_eq_u32 s80, 3
	s_cselect_b32 s81, 0xc000, s81
	v_add_u32_e32 v242, s81, v253
	s_add_i32 s72, s7, 1
	s_mul_hi_u32 s80, s72, 0x33333334
	s_mul_i32 s80, s80, 5
	s_sub_u32 s80, s72, s80
	s_lshl_b32 s81, s80, 13
	s_cmp_eq_u32 s80, 3
	s_cselect_b32 s81, 0xe000, s81
	s_cmp_eq_u32 s80, 4
	s_cselect_b32 s81, 0x10000, s81
	v_add_u32_e32 v243, s81, v221
	ds_read_b64_tr_b16 v[160:161], v242 offset:24576
	ds_read_b64_tr_b16 v[162:163], v242 offset:25088
	ds_read_b64_tr_b16 v[164:165], v242 offset:25600
	ds_read_b64_tr_b16 v[166:167], v242 offset:26112
	ds_read_b64_tr_b16 v[168:169], v242 offset:26624
	ds_read_b64_tr_b16 v[170:171], v242 offset:27136
	ds_read_b64_tr_b16 v[172:173], v242 offset:27648
	ds_read_b64_tr_b16 v[174:175], v242 offset:28160
	v_mfma_f32_32x32x16_bf16 v[80:95], v[128:131], v[96:99], 0
	v_add_f32_e32 v204, v204, v32
	v_add_f32_e32 v205, v205, v33
	v_add_f32_e32 v208, v208, v34
	v_add_f32_e32 v209, v209, v35
	v_cvt_pk_bf16_f32 v112, v32, v33
	v_cvt_pk_bf16_f32 v113, v34, v35
	v_mfma_f32_32x32x16_bf16 v[48:63], v[132:135], v[96:99], 0
	v_add_f32_e32 v204, v204, v36
	v_add_f32_e32 v205, v205, v37
	v_add_f32_e32 v208, v208, v38
	v_add_f32_e32 v209, v209, v39
	v_cvt_pk_bf16_f32 v114, v36, v37
	v_cvt_pk_bf16_f32 v115, v38, v39
	v_mfma_f32_32x32x16_bf16 v[80:95], v[136:139], v[100:103], v[80:95]
	v_add_f32_e32 v204, v204, v40
	v_add_f32_e32 v205, v205, v41
	v_add_f32_e32 v208, v208, v42
	v_add_f32_e32 v209, v209, v43
	v_cvt_pk_bf16_f32 v116, v40, v41
	v_cvt_pk_bf16_f32 v117, v42, v43
	v_mfma_f32_32x32x16_bf16 v[48:63], v[140:143], v[100:103], v[48:63]
	v_add_f32_e32 v204, v204, v44
	v_add_f32_e32 v205, v205, v45
	v_add_f32_e32 v208, v208, v46
	v_add_f32_e32 v209, v209, v47
	v_cvt_pk_bf16_f32 v118, v44, v45
	v_cvt_pk_bf16_f32 v119, v46, v47
	v_mfma_f32_32x32x16_bf16 v[80:95], v[144:147], v[104:107], v[80:95]
	v_add_f32_e32 v204, v204, v64
	v_add_f32_e32 v205, v205, v65
	v_add_f32_e32 v208, v208, v66
	v_add_f32_e32 v209, v209, v67
	v_cvt_pk_bf16_f32 v120, v64, v65
	v_cvt_pk_bf16_f32 v121, v66, v67
	v_mfma_f32_32x32x16_bf16 v[48:63], v[148:151], v[104:107], v[48:63]
	v_add_f32_e32 v204, v204, v68
	v_add_f32_e32 v205, v205, v69
	v_add_f32_e32 v208, v208, v70
	v_add_f32_e32 v209, v209, v71
	v_cvt_pk_bf16_f32 v122, v68, v69
	v_cvt_pk_bf16_f32 v123, v70, v71
	v_mfma_f32_32x32x16_bf16 v[80:95], v[152:155], v[108:111], v[80:95]
	v_add_f32_e32 v204, v204, v72
	v_add_f32_e32 v205, v205, v73
	v_add_f32_e32 v208, v208, v74
	v_add_f32_e32 v209, v209, v75
	v_cvt_pk_bf16_f32 v124, v72, v73
	v_cvt_pk_bf16_f32 v125, v74, v75
	v_mfma_f32_32x32x16_bf16 v[48:63], v[156:159], v[108:111], v[48:63]
	v_add_f32_e32 v204, v204, v76
	v_add_f32_e32 v205, v205, v77
	v_add_f32_e32 v208, v208, v78
	v_add_f32_e32 v209, v209, v79
	v_cvt_pk_bf16_f32 v126, v76, v77
	v_cvt_pk_bf16_f32 v127, v78, v79
	ds_read_b64_tr_b16 v[176:177], v242 offset:28672
	ds_read_b64_tr_b16 v[178:179], v242 offset:29184
	ds_read_b64_tr_b16 v[180:181], v242 offset:29696
	ds_read_b64_tr_b16 v[182:183], v242 offset:30208
	ds_read_b64_tr_b16 v[184:185], v242 offset:30720
	ds_read_b64_tr_b16 v[186:187], v242 offset:31232
	ds_read_b64_tr_b16 v[188:189], v242 offset:31744
	s_waitcnt lgkmcnt(14)
	ds_read_b64_tr_b16 v[190:191], v242 offset:32256
	s_waitcnt lgkmcnt(14)
	v_mfma_f32_32x32x16_bf16 v[0:15], v[160:163], v[112:115], v[0:15]
	v_exp_f32_e32 v80, v80
	v_exp_f32_e32 v81, v81
	v_exp_f32_e32 v82, v82
	v_exp_f32_e32 v83, v83
	s_waitcnt lgkmcnt(12)
	v_mfma_f32_32x32x16_bf16 v[0:15], v[164:167], v[116:119], v[0:15]
	v_exp_f32_e32 v84, v84
	v_exp_f32_e32 v85, v85
	v_exp_f32_e32 v86, v86
	v_exp_f32_e32 v87, v87
	s_waitcnt lgkmcnt(10)
	v_mfma_f32_32x32x16_bf16 v[0:15], v[168:171], v[120:123], v[0:15]
	v_exp_f32_e32 v88, v88
	v_exp_f32_e32 v89, v89
	v_exp_f32_e32 v90, v90
	v_exp_f32_e32 v91, v91
	ds_read_b128 v[128:131], v243
	ds_read_b128 v[132:135], v243 offset:512
	s_waitcnt lgkmcnt(10)
	v_mfma_f32_32x32x16_bf16 v[0:15], v[172:175], v[124:127], v[0:15]
	v_exp_f32_e32 v92, v92
	v_exp_f32_e32 v93, v93
	v_exp_f32_e32 v94, v94
	v_exp_f32_e32 v95, v95
	ds_read_b128 v[136:139], v243 offset:2048
	ds_read_b128 v[140:143], v243 offset:2560
	s_waitcnt lgkmcnt(10)
	v_mfma_f32_32x32x16_bf16 v[16:31], v[176:179], v[112:115], v[16:31]
	v_exp_f32_e32 v48, v48
	v_exp_f32_e32 v49, v49
	v_exp_f32_e32 v50, v50
	v_exp_f32_e32 v51, v51
	ds_read_b128 v[144:147], v243 offset:4096
	ds_read_b128 v[148:151], v243 offset:4608
	s_waitcnt lgkmcnt(10)
	v_mfma_f32_32x32x16_bf16 v[16:31], v[180:183], v[116:119], v[16:31]
	v_exp_f32_e32 v52, v52
	v_exp_f32_e32 v53, v53
	v_exp_f32_e32 v54, v54
	v_exp_f32_e32 v55, v55
	ds_read_b128 v[152:155], v243 offset:6144
	ds_read_b128 v[156:159], v243 offset:6656
	s_waitcnt lgkmcnt(10)
	v_mfma_f32_32x32x16_bf16 v[16:31], v[184:187], v[120:123], v[16:31]
	v_exp_f32_e32 v56, v56
	v_exp_f32_e32 v57, v57
	v_exp_f32_e32 v58, v58
	v_exp_f32_e32 v59, v59
	s_waitcnt lgkmcnt(8)
	v_mfma_f32_32x32x16_bf16 v[16:31], v[188:191], v[124:127], v[16:31]
	v_exp_f32_e32 v60, v60
	v_exp_f32_e32 v61, v61
	v_exp_f32_e32 v62, v62
	v_exp_f32_e32 v63, v63
	s_waitcnt lgkmcnt(0)
	s_and_b64 vcc, exec, s[82:83]
	s_cbranch_vccz .Lgo_w0
	s_waitcnt vmcnt(4)
	s_branch .Lgo_w1

; template <bool NOMAX> ...
;     ...
;         for (int t = 1; t < NF; t += 2) {
;             ATT_STEP(t, kreg, vreg, kregB, vregB, e0, e1, c0, c1);
;             if (t + 1 < NF) ATT_STEP(t + 1, kregB, vregB, kreg, vreg, c0, c1, e0, e1);
.Lgo_w1:
	s_barrier
	s_add_i32 s7, s7, 1
	s_cmp_ge_i32 s7, s71
	s_cbranch_scc1 .Lg_drainB
	s_add_i32 s96, s7, 4
	s_cmp_lt_i32 s96, s71
	s_cselect_b64 s[82:83], -1, 0
	s_cbranch_scc0 .Lge_nk
	s_cmp_lg_u32 s96, 4
	s_cbranch_scc1 .Lge_ks
	v_mad_i64_i32 v[244:245], s[80:81], s84, v215, v[198:199]
	v_ashrrev_i32_e32 v243, 31, v248
	v_mov_b32_e32 v242, v248
	v_lshl_add_u64 v[244:245], v[242:243], 0, v[244:245]

.Lge_nv:
	s_add_i32 s72, s7, 3
	s_and_b32 s80, s72, 3
	s_lshl_b32 s81, s80, 13
	s_cmp_eq_u32 s80, 2
	s_cselect_b32 s81, 0x6000, s81
	s_cmp_eq_u32 s80, 3
	s_cselect_b32 s81, 0xc000, s81
	v_add_u32_e32 v242, s81, v253
	s_add_i32 s72, s7, 1
	s_mul_hi_u32 s80, s72, 0x33333334
	s_mul_i32 s80, s80, 5
	s_sub_u32 s80, s72, s80
	s_lshl_b32 s81, s80, 13
	s_cmp_eq_u32 s80, 3
	s_cselect_b32 s81, 0xe000, s81
	s_cmp_eq_u32 s80, 4
	s_cselect_b32 s81, 0x10000, s81
	v_add_u32_e32 v243, s81, v221
	ds_read_b64_tr_b16 v[160:161], v242 offset:24576
	ds_read_b64_tr_b16 v[162:163], v242 offset:25088
	ds_read_b64_tr_b16 v[164:165], v242 offset:25600
	ds_read_b64_tr_b16 v[166:167], v242 offset:26112
	ds_read_b64_tr_b16 v[168:169], v242 offset:26624
	ds_read_b64_tr_b16 v[170:171], v242 offset:27136
	ds_read_b64_tr_b16 v[172:173], v242 offset:27648
	ds_read_b64_tr_b16 v[174:175], v242 offset:28160
	v_mfma_f32_32x32x16_bf16 v[32:47], v[128:131], v[96:99], 0
	v_add_f32_e32 v204, v204, v80
	v_add_f32_e32 v205, v205, v81
	v_add_f32_e32 v208, v208, v82
	v_add_f32_e32 v209, v209, v83
	v_cvt_pk_bf16_f32 v112, v80, v81
	v_cvt_pk_bf16_f32 v113, v82, v83
	v_mfma_f32_32x32x16_bf16 v[64:79], v[132:135], v[96:99], 0
	v_add_f32_e32 v204, v204, v84
	v_add_f32_e32 v205, v205, v85
	v_add_f32_e32 v208, v208, v86
	v_add_f32_e32 v209, v209, v87
	v_cvt_pk_bf16_f32 v114, v84, v85
	v_cvt_pk_bf16_f32 v115, v86, v87
	v_mfma_f32_32x32x16_bf16 v[32:47], v[136:139], v[100:103], v[32:47]
	v_add_f32_e32 v204, v204, v88
	v_add_f32_e32 v205, v205, v89
	v_add_f32_e32 v208, v208, v90
	v_add_f32_e32 v209, v209, v91
	v_cvt_pk_bf16_f32 v116, v88, v89
	v_cvt_pk_bf16_f32 v117, v90, v91
	v_mfma_f32_32x32x16_bf16 v[64:79], v[140:143], v[100:103], v[64:79]
	v_add_f32_e32 v204, v204, v92
	v_add_f32_e32 v205, v205, v93
	v_add_f32_e32 v208, v208, v94
	v_add_f32_e32 v209, v209, v95
	v_cvt_pk_bf16_f32 v118, v92, v93
	v_cvt_pk_bf16_f32 v119, v94, v95
	v_mfma_f32_32x32x16_bf16 v[32:47], v[144:147], v[104:107], v[32:47]
	v_add_f32_e32 v204, v204, v48
	v_add_f32_e32 v205, v205, v49
	v_add_f32_e32 v208, v208, v50
	v_add_f32_e32 v209, v209, v51
	v_cvt_pk_bf16_f32 v120, v48, v49
	v_cvt_pk_bf16_f32 v121, v50, v51
	v_mfma_f32_32x32x16_bf16 v[64:79], v[148:151], v[104:107], v[64:79]
	v_add_f32_e32 v204, v204, v52
	v_add_f32_e32 v205, v205, v53
	v_add_f32_e32 v208, v208, v54
	v_add_f32_e32 v209, v209, v55
	v_cvt_pk_bf16_f32 v122, v52, v53
	v_cvt_pk_bf16_f32 v123, v54, v55
	v_mfma_f32_32x32x16_bf16 v[32:47], v[152:155], v[108:111], v[32:47]
	v_add_f32_e32 v204, v204, v56
	v_add_f32_e32 v205, v205, v57
	v_add_f32_e32 v208, v208, v58
	v_add_f32_e32 v209, v209, v59
	v_cvt_pk_bf16_f32 v124, v56, v57
	v_cvt_pk_bf16_f32 v125, v58, v59
	v_mfma_f32_32x32x16_bf16 v[64:79], v[156:159], v[108:111], v[64:79]
	v_add_f32_e32 v204, v204, v60
	v_add_f32_e32 v205, v205, v61
	v_add_f32_e32 v208, v208, v62
	v_add_f32_e32 v209, v209, v63
	v_cvt_pk_bf16_f32 v126, v60, v61
	v_cvt_pk_bf16_f32 v127, v62, v63
	ds_read_b64_tr_b16 v[176:177], v242 offset:28672
	ds_read_b64_tr_b16 v[178:179], v242 offset:29184
	ds_read_b64_tr_b16 v[180:181], v242 offset:29696
	ds_read_b64_tr_b16 v[182:183], v242 offset:30208
	ds_read_b64_tr_b16 v[184:185], v242 offset:30720
	ds_read_b64_tr_b16 v[186:187], v242 offset:31232
	ds_read_b64_tr_b16 v[188:189], v242 offset:31744
	s_waitcnt lgkmcnt(14)
	ds_read_b64_tr_b16 v[190:191], v242 offset:32256
	s_waitcnt lgkmcnt(14)
	v_mfma_f32_32x32x16_bf16 v[0:15], v[160:163], v[112:115], v[0:15]
	v_exp_f32_e32 v32, v32
	v_exp_f32_e32 v33, v33
	v_exp_f32_e32 v34, v34
	v_exp_f32_e32 v35, v35
	s_waitcnt lgkmcnt(12)
	v_mfma_f32_32x32x16_bf16 v[0:15], v[164:167], v[116:119], v[0:15]
	v_exp_f32_e32 v36, v36
	v_exp_f32_e32 v37, v37
	v_exp_f32_e32 v38, v38
	v_exp_f32_e32 v39, v39
	s_waitcnt lgkmcnt(10)
	v_mfma_f32_32x32x16_bf16 v[0:15], v[168:171], v[120:123], v[0:15]
	v_exp_f32_e32 v40, v40
	v_exp_f32_e32 v41, v41
	v_exp_f32_e32 v42, v42
	v_exp_f32_e32 v43, v43
	ds_read_b128 v[128:131], v243
	ds_read_b128 v[132:135], v243 offset:512
	s_waitcnt lgkmcnt(10)
	v_mfma_f32_32x32x16_bf16 v[0:15], v[172:175], v[124:127], v[0:15]
	v_exp_f32_e32 v44, v44
	v_exp_f32_e32 v45, v45
	v_exp_f32_e32 v46, v46
	v_exp_f32_e32 v47, v47
	ds_read_b128 v[136:139], v243 offset:2048
	ds_read_b128 v[140:143], v243 offset:2560
	s_waitcnt lgkmcnt(10)
	v_mfma_f32_32x32x16_bf16 v[16:31], v[176:179], v[112:115], v[16:31]
	v_exp_f32_e32 v64, v64
	v_exp_f32_e32 v65, v65
	v_exp_f32_e32 v66, v66
	v_exp_f32_e32 v67, v67
	ds_read_b128 v[144:147], v243 offset:4096
	ds_read_b128 v[148:151], v243 offset:4608
	s_waitcnt lgkmcnt(10)
	v_mfma_f32_32x32x16_bf16 v[16:31], v[180:183], v[116:119], v[16:31]
	v_exp_f32_e32 v68, v68
	v_exp_f32_e32 v69, v69
	v_exp_f32_e32 v70, v70
	v_exp_f32_e32 v71, v71
	ds_read_b128 v[152:155], v243 offset:6144
	ds_read_b128 v[156:159], v243 offset:6656
	s_waitcnt lgkmcnt(10)
	v_mfma_f32_32x32x16_bf16 v[16:31], v[184:187], v[120:123], v[16:31]
	v_exp_f32_e32 v72, v72
	v_exp_f32_e32 v73, v73
	v_exp_f32_e32 v74, v74
	v_exp_f32_e32 v75, v75
	s_waitcnt lgkmcnt(8)
	v_mfma_f32_32x32x16_bf16 v[16:31], v[188:191], v[124:127], v[16:31]
	v_exp_f32_e32 v76, v76
	v_exp_f32_e32 v77, v77
	v_exp_f32_e32 v78, v78
	v_exp_f32_e32 v79, v79
	s_waitcnt lgkmcnt(0)
	s_and_b64 vcc, exec, s[82:83]
	s_cbranch_vccz .Lge_w0
	s_waitcnt vmcnt(4)
	s_branch .Lge_w1

; #define ATT_LAS __attribute__((address_space(3)))
; __device__ __forceinline__ unsigned pk_bf16(float lo, float hi) { unsigned r; asm volatile("v_cvt_pk_bf16_f32 %0, %1, %2" : "=v"(r) : "v"(lo), "v"(hi)); return r; }
; template <bool NOMAX> ...
;     ...
;         if ((NF - 1) & 1) { e0 = c0; e1 = c1; }
;     ...
;         { u32x4 pw[4]; float sacc = 0.f;
; #pragma unroll
;           for (int r = 0; r < 16; ++r) sacc += e0[r] + e1[r];
;           lsum += sacc;
; #pragma unroll
;           for (int j = 0; j < 4; ++j) { pw[0][j] = pk_bf16(e0[2 * j], e0[2 * j + 1]); pw[1][j] = pk_bf16(e0[8 + 2 * j], e0[8 + 2 * j + 1]);
;                                         pw[2][j] = pk_bf16(e1[2 * j], e1[2 * j + 1]); pw[3][j] = pk_bf16(e1[8 + 2 * j], e1[8 + 2 * j + 1]); }
;           const ATT_LAS unsigned char* vb = ATT_VBUF((NF - 1) & 1) + vlane;
; #pragma unroll
;           for (int s = 0; s < 4; ++s) { const bf16x8 pa = __builtin_bit_cast(bf16x8, pw[s]);
;               { const s16x4 lo = vtr(vb + s * 1024), h4 = vtr(vb + s * 1024 + 512); const bf16x8 vf = (bf16x8){lo[0], lo[1], lo[2], lo[3], h4[0], h4[1], h4[2], h4[3]};
;                 o0 = __builtin_amdgcn_mfma_f32_32x32x16_bf16(vf, pa, o0, 0, 0, 0); }
;               { const s16x4 lo = vtr(vb + 4096 + s * 1024), h4 = vtr(vb + 4096 + s * 1024 + 512); const bf16x8 vf = (bf16x8){lo[0], lo[1], lo[2], lo[3], h4[0], h4[1], h4[2], h4[3]};
;                 o1 = __builtin_amdgcn_mfma_f32_32x32x16_bf16(vf, pa, o1, 0, 0, 0); } }
;         }
;         __syncthreads();
.Lge_w1:
	s_barrier
	s_add_i32 s7, s7, 1
	s_cmp_lt_i32 s7, s71
	s_cbranch_scc1 .Lg_loop
	s_add_i32 s72, s7, 3
	s_and_b32 s80, s72, 3
	s_lshl_b32 s81, s80, 13
	s_cmp_eq_u32 s80, 2
	s_cselect_b32 s81, 0x6000, s81
	s_cmp_eq_u32 s80, 3
	s_cselect_b32 s81, 0xc000, s81
	v_add_u32_e32 v242, s81, v253
	ds_read_b64_tr_b16 v[160:161], v242 offset:24576
	ds_read_b64_tr_b16 v[162:163], v242 offset:25088
	ds_read_b64_tr_b16 v[164:165], v242 offset:25600
	ds_read_b64_tr_b16 v[166:167], v242 offset:26112
	ds_read_b64_tr_b16 v[168:169], v242 offset:26624
	ds_read_b64_tr_b16 v[170:171], v242 offset:27136
	ds_read_b64_tr_b16 v[172:173], v242 offset:27648
	ds_read_b64_tr_b16 v[174:175], v242 offset:28160
	v_add_f32_e32 v204, v204, v32
	v_add_f32_e32 v205, v205, v33
	v_add_f32_e32 v208, v208, v34
	v_add_f32_e32 v209, v209, v35
	v_add_f32_e32 v204, v204, v36
	v_add_f32_e32 v205, v205, v37
	v_add_f32_e32 v208, v208, v38
	v_add_f32_e32 v209, v209, v39
	v_add_f32_e32 v204, v204, v40
	v_add_f32_e32 v205, v205, v41
	v_add_f32_e32 v208, v208, v42
	v_add_f32_e32 v209, v209, v43
	v_add_f32_e32 v204, v204, v44
	v_add_f32_e32 v205, v205, v45
	v_add_f32_e32 v208, v208, v46
	v_add_f32_e32 v209, v209, v47
	v_add_f32_e32 v204, v204, v64
	v_add_f32_e32 v205, v205, v65
	v_add_f32_e32 v208, v208, v66
	v_add_f32_e32 v209, v209, v67
	v_add_f32_e32 v204, v204, v68
	v_add_f32_e32 v205, v205, v69
	v_add_f32_e32 v208, v208, v70
	v_add_f32_e32 v209, v209, v71
	v_add_f32_e32 v204, v204, v72
	v_add_f32_e32 v205, v205, v73
	v_add_f32_e32 v208, v208, v74
	v_add_f32_e32 v209, v209, v75
	v_add_f32_e32 v204, v204, v76
	v_add_f32_e32 v205, v205, v77
	v_add_f32_e32 v208, v208, v78
	v_add_f32_e32 v209, v209, v79
	v_cvt_pk_bf16_f32 v112, v32, v33
	v_cvt_pk_bf16_f32 v113, v34, v35
	v_cvt_pk_bf16_f32 v114, v36, v37
	v_cvt_pk_bf16_f32 v115, v38, v39
	v_cvt_pk_bf16_f32 v116, v40, v41
	v_cvt_pk_bf16_f32 v117, v42, v43
	v_cvt_pk_bf16_f32 v118, v44, v45
	v_cvt_pk_bf16_f32 v119, v46, v47
	v_cvt_pk_bf16_f32 v120, v64, v65
	v_cvt_pk_bf16_f32 v121, v66, v67
	v_cvt_pk_bf16_f32 v122, v68, v69
	v_cvt_pk_bf16_f32 v123, v70, v71
	v_cvt_pk_bf16_f32 v124, v72, v73
	v_cvt_pk_bf16_f32 v125, v74, v75
	v_cvt_pk_bf16_f32 v126, v76, v77
	v_cvt_pk_bf16_f32 v127, v78, v79
	ds_read_b64_tr_b16 v[176:177], v242 offset:28672
	ds_read_b64_tr_b16 v[178:179], v242 offset:29184
	ds_read_b64_tr_b16 v[180:181], v242 offset:29696
	ds_read_b64_tr_b16 v[182:183], v242 offset:30208
	ds_read_b64_tr_b16 v[184:185], v242 offset:30720
	ds_read_b64_tr_b16 v[186:187], v242 offset:31232
	ds_read_b64_tr_b16 v[188:189], v242 offset:31744
	s_waitcnt lgkmcnt(14)
	ds_read_b64_tr_b16 v[190:191], v242 offset:32256
	s_waitcnt lgkmcnt(0)
	v_mfma_f32_32x32x16_bf16 v[0:15], v[160:163], v[112:115], v[0:15]
	v_mfma_f32_32x32x16_bf16 v[0:15], v[164:167], v[116:119], v[0:15]
	v_mfma_f32_32x32x16_bf16 v[0:15], v[168:171], v[120:123], v[0:15]
	v_mfma_f32_32x32x16_bf16 v[0:15], v[172:175], v[124:127], v[0:15]
	v_mfma_f32_32x32x16_bf16 v[16:31], v[176:179], v[112:115], v[16:31]
	v_mfma_f32_32x32x16_bf16 v[16:31], v[180:183], v[116:119], v[16:31]
	v_mfma_f32_32x32x16_bf16 v[16:31], v[184:187], v[120:123], v[16:31]
	v_mfma_f32_32x32x16_bf16 v[16:31], v[188:191], v[124:127], v[16:31]
	s_branch .Lg_done
.Lg_drainB:
	s_add_i32 s72, s7, 3
	s_and_b32 s80, s72, 3
	s_lshl_b32 s81, s80, 13
	s_cmp_eq_u32 s80, 2
	s_cselect_b32 s81, 0x6000, s81
	s_cmp_eq_u32 s80, 3
	s_cselect_b32 s81, 0xc000, s81
	v_add_u32_e32 v242, s81, v253
	ds_read_b64_tr_b16 v[160:161], v242 offset:24576
	ds_read_b64_tr_b16 v[162:163], v242 offset:25088
	ds_read_b64_tr_b16 v[164:165], v242 offset:25600
	ds_read_b64_tr_b16 v[166:167], v242 offset:26112
	ds_read_b64_tr_b16 v[168:169], v242 offset:26624
	ds_read_b64_tr_b16 v[170:171], v242 offset:27136
	ds_read_b64_tr_b16 v[172:173], v242 offset:27648
	ds_read_b64_tr_b16 v[174:175], v242 offset:28160
	v_add_f32_e32 v204, v204, v80
	v_add_f32_e32 v205, v205, v81
	v_add_f32_e32 v208, v208, v82
	v_add_f32_e32 v209, v209, v83
	v_add_f32_e32 v204, v204, v84
	v_add_f32_e32 v205, v205, v85
	v_add_f32_e32 v208, v208, v86
	v_add_f32_e32 v209, v209, v87
	v_add_f32_e32 v204, v204, v88
	v_add_f32_e32 v205, v205, v89
	v_add_f32_e32 v208, v208, v90
	v_add_f32_e32 v209, v209, v91
	v_add_f32_e32 v204, v204, v92
	v_add_f32_e32 v205, v205, v93
	v_add_f32_e32 v208, v208, v94
	v_add_f32_e32 v209, v209, v95
	v_add_f32_e32 v204, v204, v48
	v_add_f32_e32 v205, v205, v49
	v_add_f32_e32 v208, v208, v50
	v_add_f32_e32 v209, v209, v51
	v_add_f32_e32 v204, v204, v52
	v_add_f32_e32 v205, v205, v53
	v_add_f32_e32 v208, v208, v54
	v_add_f32_e32 v209, v209, v55
	v_add_f32_e32 v204, v204, v56
	v_add_f32_e32 v205, v205, v57
	v_add_f32_e32 v208, v208, v58
	v_add_f32_e32 v209, v209, v59
	v_add_f32_e32 v204, v204, v60
	v_add_f32_e32 v205, v205, v61
	v_add_f32_e32 v208, v208, v62
	v_add_f32_e32 v209, v209, v63
	v_cvt_pk_bf16_f32 v112, v80, v81
	v_cvt_pk_bf16_f32 v113, v82, v83
	v_cvt_pk_bf16_f32 v114, v84, v85
	v_cvt_pk_bf16_f32 v115, v86, v87
	v_cvt_pk_bf16_f32 v116, v88, v89
	v_cvt_pk_bf16_f32 v117, v90, v91
	v_cvt_pk_bf16_f32 v118, v92, v93
	v_cvt_pk_bf16_f32 v119, v94, v95
	v_cvt_pk_bf16_f32 v120, v48, v49
	v_cvt_pk_bf16_f32 v121, v50, v51
	v_cvt_pk_bf16_f32 v122, v52, v53
	v_cvt_pk_bf16_f32 v123, v54, v55
	v_cvt_pk_bf16_f32 v124, v56, v57
	v_cvt_pk_bf16_f32 v125, v58, v59
	v_cvt_pk_bf16_f32 v126, v60, v61
	v_cvt_pk_bf16_f32 v127, v62, v63
	ds_read_b64_tr_b16 v[176:177], v242 offset:28672
	ds_read_b64_tr_b16 v[178:179], v242 offset:29184
	ds_read_b64_tr_b16 v[180:181], v242 offset:29696
	ds_read_b64_tr_b16 v[182:183], v242 offset:30208
	ds_read_b64_tr_b16 v[184:185], v242 offset:30720
	ds_read_b64_tr_b16 v[186:187], v242 offset:31232
	ds_read_b64_tr_b16 v[188:189], v242 offset:31744
	s_waitcnt lgkmcnt(14)
	ds_read_b64_tr_b16 v[190:191], v242 offset:32256
	s_waitcnt lgkmcnt(0)
	v_mfma_f32_32x32x16_bf16 v[0:15], v[160:163], v[112:115], v[0:15]
	v_mfma_f32_32x32x16_bf16 v[0:15], v[164:167], v[116:119], v[0:15]
	v_mfma_f32_32x32x16_bf16 v[0:15], v[168:171], v[120:123], v[0:15]
	v_mfma_f32_32x32x16_bf16 v[0:15], v[172:175], v[124:127], v[0:15]
	v_mfma_f32_32x32x16_bf16 v[16:31], v[176:179], v[112:115], v[16:31]
	v_mfma_f32_32x32x16_bf16 v[16:31], v[180:183], v[116:119], v[16:31]
	v_mfma_f32_32x32x16_bf16 v[16:31], v[184:187], v[120:123], v[16:31]
	v_mfma_f32_32x32x16_bf16 v[16:31], v[188:191], v[124:127], v[16:31]
